# GEMM phases: one static s_setprio 1 for the second workgroup of every CU (the arbitration loser by age)
# baseline (speedup 1.0000x reference)
.Lg2_ff2_entry:
	s_waitcnt vmcnt(0) lgkmcnt(0)
	s_barrier
	v_mov_b32_e32 v2, 0x10200
	ds_read_b64 v[2:3], v2
	v_readlane_b32 s0, v246, 0
	v_lshrrev_b32_e32 v4, 6, v163
	v_and_b32_e32 v5, 63, v163
	s_and_b32 s1, s0, 7
	s_lshr_b32 s0, s0, 3
	s_lshr_b32 s68, s0, 3
	s_and_b32 s0, s0, 7
	s_lshl_b32 s0, s0, 3
	s_add_i32 s0, s0, s1
	s_cmp_lt_u32 s0, 32
	s_cselect_b32 s43, 1, 0
	s_min_u32 s1, s0, 32
	s_lshl_b32 s0, s0, 4
	s_add_i32 s0, s0, s1
	s_lshl_b32 s42, s0, 4
	v_readfirstlane_b32 s70, v4
	v_and_b32_e32 v6, 15, v5
	v_lshrrev_b32_e32 v7, 4, v5
	s_waitcnt lgkmcnt(0)
	v_readfirstlane_b32 s66, v2
	v_readfirstlane_b32 s67, v3
	s_lshl_b32 s62, s70, 10
	v_and_b32_e32 v8, 7, v6
	v_xor_b32_e32 v9, v7, v8
	v_lshlrev_b32_e32 v9, 4, v9
	v_lshl_add_u32 v156, v6, 7, v9
	v_add_u32_e32 v10, 4, v7
	v_xor_b32_e32 v10, v10, v8
	v_lshlrev_b32_e32 v10, 4, v10
	v_lshl_add_u32 v157, v6, 7, v10
	v_add_u32_e32 v158, 0x8800, v156
	v_add_u32_e32 v159, 0x8800, v157
	v_lshrrev_b32_e32 v11, 3, v163
	v_and_b32_e32 v12, 7, v163
	v_and_b32_e32 v13, 7, v11
	v_xor_b32_e32 v12, v12, v13
	v_lshlrev_b32_e32 v12, 4, v12
	s_mov_b32 s2, 0x2000
	v_mul_lo_u32 v11, v11, s2
	v_add_u32_e32 v162, v11, v12
	v_lshrrev_b32_e32 v11, 4, v163
	v_and_b32_e32 v12, 15, v163
	v_xor_b32_e32 v13, v12, v11
	v_lshlrev_b32_e32 v13, 4, v13
	v_lshl_add_u32 v247, v11, 8, v13
	s_mov_b32 s2, 0x800
	v_mul_lo_u32 v11, v11, s2
	v_lshl_add_u32 v252, v12, 4, v11
	v_add_u32_e32 v255, 0x8000, v247
	v_lshlrev_b32_e32 v11, 1, v4
	s_mov_b32 s2, 0x20000
	v_mul_lo_u32 v12, v11, s2
	v_lshl_add_u32 v160, v5, 4, v12
	v_add_u32_e32 v161, 0x20000, v160
	v_lshrrev_b32_e32 v12, 1, v7
	v_lshl_add_u32 v12, v11, 1, v12
	v_and_b32_e32 v13, 1, v7
	v_lshlrev_b32_e32 v13, 3, v13
	v_lshl_add_u32 v14, v6, 8, v13
	v_xor_b32_e32 v15, v12, v6
	v_lshlrev_b32_e32 v15, 4, v15
	v_add_u32_e32 v212, v14, v15
	v_add_u32_e32 v12, 2, v12
	v_xor_b32_e32 v15, v12, v6
	v_lshlrev_b32_e32 v15, 4, v15
	v_add_u32_e32 v213, v14, v15
	v_add_u32_e32 v253, 0x8000, v212
	v_add_u32_e32 v254, 0x8000, v213
	s_cmp_lt_u32 s68, 4
	s_cbranch_scc1 .Lg2_ff2_noprio
	s_setprio 1
.Lg2_ff2_noprio:
	s_mov_b32 s64, 0

.Lg2_ff2_exit:
	s_setprio 0
	v_mov_b32_e32 v2, 0x10200
	v_mov_b32_e32 v4, s66
	v_mov_b32_e32 v5, s67
	ds_write_b64 v2, v[4:5]
	v_mov_b32_e32 v1, 0
	s_waitcnt vmcnt(0) lgkmcnt(0)

.Lg2_ff1_entry:
	s_waitcnt vmcnt(0) lgkmcnt(0)
	s_barrier
	v_mov_b32_e32 v2, 0x10200
	ds_read_b64 v[2:3], v2
	v_readlane_b32 s0, v246, 0
	v_lshrrev_b32_e32 v4, 6, v163
	v_and_b32_e32 v5, 63, v163
	s_and_b32 s1, s0, 7
	s_lshr_b32 s0, s0, 3
	s_lshr_b32 s68, s0, 3
	s_and_b32 s0, s0, 7
	s_lshl_b32 s0, s0, 3
	s_add_i32 s0, s0, s1
	s_cmp_lt_u32 s0, 32
	s_cselect_b32 s43, 1, 0
	s_min_u32 s1, s0, 32
	s_lshl_b32 s0, s0, 4
	s_add_i32 s0, s0, s1
	s_lshl_b32 s42, s0, 4
	v_readfirstlane_b32 s70, v4
	v_and_b32_e32 v6, 15, v5
	v_lshrrev_b32_e32 v7, 4, v5
	s_waitcnt lgkmcnt(0)
	v_readfirstlane_b32 s66, v2
	v_readfirstlane_b32 s67, v3
	s_lshl_b32 s62, s70, 10
	v_and_b32_e32 v8, 7, v6
	v_xor_b32_e32 v9, v7, v8
	v_lshlrev_b32_e32 v9, 4, v9
	v_lshl_add_u32 v156, v6, 7, v9
	v_add_u32_e32 v10, 4, v7
	v_xor_b32_e32 v10, v10, v8
	v_lshlrev_b32_e32 v10, 4, v10
	v_lshl_add_u32 v157, v6, 7, v10
	v_add_u32_e32 v158, 0x8800, v156
	v_add_u32_e32 v159, 0x8800, v157
	v_lshrrev_b32_e32 v11, 3, v163
	v_and_b32_e32 v12, 7, v163
	v_and_b32_e32 v13, 7, v11
	v_xor_b32_e32 v12, v12, v13
	v_lshlrev_b32_e32 v12, 4, v12
	s_mov_b32 s2, 0x800
	v_mul_lo_u32 v11, v11, s2
	v_add_u32_e32 v162, v11, v12
	v_lshrrev_b32_e32 v11, 4, v163
	v_and_b32_e32 v12, 15, v163
	v_xor_b32_e32 v13, v12, v11
	v_lshlrev_b32_e32 v13, 4, v13
	v_lshl_add_u32 v247, v11, 8, v13
	s_mov_b32 s2, 0x2000
	v_mul_lo_u32 v11, v11, s2
	v_lshl_add_u32 v252, v12, 4, v11
	v_add_u32_e32 v255, 0x8000, v247
	v_lshlrev_b32_e32 v11, 1, v4
	s_mov_b32 s2, 0x8000
	v_mul_lo_u32 v12, v11, s2
	v_lshl_add_u32 v160, v5, 4, v12
	v_add_u32_e32 v161, 0x8000, v160
	v_lshrrev_b32_e32 v12, 1, v7
	v_lshl_add_u32 v12, v11, 1, v12
	v_and_b32_e32 v13, 1, v7
	v_lshlrev_b32_e32 v13, 3, v13
	v_lshl_add_u32 v14, v6, 8, v13
	v_xor_b32_e32 v15, v12, v6
	v_lshlrev_b32_e32 v15, 4, v15
	v_add_u32_e32 v212, v14, v15
	v_add_u32_e32 v12, 2, v12
	v_xor_b32_e32 v15, v12, v6
	v_lshlrev_b32_e32 v15, 4, v15
	v_add_u32_e32 v213, v14, v15
	v_add_u32_e32 v253, 0x8000, v212
	v_add_u32_e32 v254, 0x8000, v213
	s_cmp_lt_u32 s68, 4
	s_cbranch_scc1 .Lg2_ff1_noprio
	s_setprio 1

.Lg2_out_entry:
	s_waitcnt vmcnt(0) lgkmcnt(0)
	s_barrier
	v_mov_b32_e32 v2, 0x10200
	ds_read_b64 v[2:3], v2
	v_readlane_b32 s0, v246, 0
	v_lshrrev_b32_e32 v4, 6, v163
	v_and_b32_e32 v5, 63, v163
	s_and_b32 s1, s0, 7
	s_lshr_b32 s0, s0, 3
	s_lshr_b32 s68, s0, 3
	s_and_b32 s0, s0, 7
	s_lshl_b32 s0, s0, 3
	s_add_i32 s0, s0, s1
	s_cmp_lt_u32 s0, 32
	s_cselect_b32 s43, 1, 0
	s_min_u32 s1, s0, 32
	s_lshl_b32 s0, s0, 4
	s_add_i32 s0, s0, s1
	s_lshl_b32 s42, s0, 4
	v_readfirstlane_b32 s70, v4
	v_and_b32_e32 v6, 15, v5
	v_lshrrev_b32_e32 v7, 4, v5
	s_waitcnt lgkmcnt(0)
	v_readfirstlane_b32 s66, v2
	v_readfirstlane_b32 s67, v3
	s_lshl_b32 s62, s70, 10
	v_and_b32_e32 v8, 7, v6
	v_xor_b32_e32 v9, v7, v8
	v_lshlrev_b32_e32 v9, 4, v9
	v_lshl_add_u32 v156, v6, 7, v9
	v_add_u32_e32 v10, 4, v7
	v_xor_b32_e32 v10, v10, v8
	v_lshlrev_b32_e32 v10, 4, v10
	v_lshl_add_u32 v157, v6, 7, v10
	v_add_u32_e32 v158, 0x8800, v156
	v_add_u32_e32 v159, 0x8800, v157
	v_lshrrev_b32_e32 v11, 3, v163
	v_and_b32_e32 v12, 7, v163
	v_and_b32_e32 v13, 7, v11
	v_xor_b32_e32 v12, v12, v13
	v_lshlrev_b32_e32 v12, 4, v12
	s_mov_b32 s2, 0x800
	v_mul_lo_u32 v11, v11, s2
	v_add_u32_e32 v162, v11, v12
	v_lshrrev_b32_e32 v11, 4, v163
	v_and_b32_e32 v12, 15, v163
	v_xor_b32_e32 v13, v12, v11
	v_lshlrev_b32_e32 v13, 4, v13
	v_lshl_add_u32 v247, v11, 8, v13
	s_mov_b32 s2, 0x800
	v_mul_lo_u32 v11, v11, s2
	v_lshl_add_u32 v252, v12, 4, v11
	v_add_u32_e32 v255, 0x8000, v247
	v_lshlrev_b32_e32 v11, 1, v4
	s_mov_b32 s2, 0x8000
	v_mul_lo_u32 v12, v11, s2
	v_lshl_add_u32 v160, v5, 4, v12
	v_add_u32_e32 v161, 0x8000, v160
	v_lshrrev_b32_e32 v12, 1, v7
	v_lshl_add_u32 v12, v11, 1, v12
	v_and_b32_e32 v13, 1, v7
	v_lshlrev_b32_e32 v13, 3, v13
	v_lshl_add_u32 v14, v6, 8, v13
	v_xor_b32_e32 v15, v12, v6
	v_lshlrev_b32_e32 v15, 4, v15
	v_add_u32_e32 v212, v14, v15
	v_add_u32_e32 v12, 2, v12
	v_xor_b32_e32 v15, v12, v6
	v_lshlrev_b32_e32 v15, 4, v15
	v_add_u32_e32 v213, v14, v15
	v_add_u32_e32 v253, 0x8000, v212
	v_add_u32_e32 v254, 0x8000, v213
	s_cmp_lt_u32 s68, 4
	s_cbranch_scc1 .Lg2_out_noprio
	s_setprio 1

.Lg2_win_entry:
	s_waitcnt vmcnt(0) lgkmcnt(0)
	s_barrier
	v_mov_b32_e32 v2, 0x10200
	ds_read_b64 v[2:3], v2
	v_readlane_b32 s0, v246, 0
	v_lshrrev_b32_e32 v4, 6, v163
	v_and_b32_e32 v5, 63, v163
	s_and_b32 s1, s0, 7
	s_lshr_b32 s0, s0, 3
	s_lshr_b32 s68, s0, 3
	s_and_b32 s0, s0, 7
	s_lshl_b32 s0, s0, 3
	s_add_i32 s0, s0, s1
	s_cmp_lt_u32 s0, 32
	s_cselect_b32 s43, 1, 0
	s_min_u32 s1, s0, 32
	s_lshl_b32 s0, s0, 4
	s_add_i32 s0, s0, s1
	s_lshl_b32 s42, s0, 4
	v_readfirstlane_b32 s70, v4
	v_and_b32_e32 v6, 15, v5
	v_lshrrev_b32_e32 v7, 4, v5
	s_waitcnt lgkmcnt(0)
	v_readfirstlane_b32 s66, v2
	v_readfirstlane_b32 s67, v3
	s_lshl_b32 s62, s70, 10
	v_and_b32_e32 v8, 7, v6
	v_xor_b32_e32 v9, v7, v8
	v_lshlrev_b32_e32 v9, 4, v9
	v_lshl_add_u32 v156, v6, 7, v9
	v_add_u32_e32 v10, 4, v7
	v_xor_b32_e32 v10, v10, v8
	v_lshlrev_b32_e32 v10, 4, v10
	v_lshl_add_u32 v157, v6, 7, v10
	v_add_u32_e32 v158, 0x8800, v156
	v_add_u32_e32 v159, 0x8800, v157
	v_lshrrev_b32_e32 v11, 3, v163
	v_and_b32_e32 v12, 7, v163
	v_and_b32_e32 v13, 7, v11
	v_xor_b32_e32 v12, v12, v13
	v_lshlrev_b32_e32 v12, 4, v12
	s_mov_b32 s2, 0x800
	v_mul_lo_u32 v11, v11, s2
	v_add_u32_e32 v162, v11, v12
	v_lshrrev_b32_e32 v11, 4, v163
	v_and_b32_e32 v12, 15, v163
	v_xor_b32_e32 v13, v12, v11
	v_lshlrev_b32_e32 v13, 4, v13
	v_lshl_add_u32 v247, v11, 8, v13
	s_mov_b32 s2, 0x3900
	v_mul_lo_u32 v11, v11, s2
	v_lshl_add_u32 v252, v12, 4, v11
	v_add_u32_e32 v255, 0x8000, v247
	v_lshrrev_b32_e32 v11, 1, v4
	v_and_b32_e32 v12, 1, v4
	v_lshl_add_u32 v11, v11, 2, v12
	s_mov_b32 s2, 0x8000
	v_mul_lo_u32 v12, v11, s2
	v_lshl_add_u32 v160, v5, 4, v12
	v_add_u32_e32 v161, 0x10000, v160
	v_lshrrev_b32_e32 v12, 1, v7
	v_lshl_add_u32 v12, v11, 1, v12
	v_and_b32_e32 v13, 1, v7
	v_lshlrev_b32_e32 v13, 3, v13
	v_lshl_add_u32 v14, v6, 8, v13
	v_xor_b32_e32 v15, v12, v6
	v_lshlrev_b32_e32 v15, 4, v15
	v_add_u32_e32 v212, v14, v15
	v_add_u32_e32 v12, 4, v12
	v_xor_b32_e32 v15, v12, v6
	v_lshlrev_b32_e32 v15, 4, v15
	v_add_u32_e32 v213, v14, v15
	v_add_u32_e32 v253, 0x8000, v212
	v_add_u32_e32 v254, 0x8000, v213
	s_cmp_lt_u32 s68, 4
	s_cbranch_scc1 .Lg2_win_noprio
	s_setprio 1

.Lg2_win_exit:
	s_setprio 0
	v_mov_b32_e32 v2, 0x10200
	v_mov_b32_e32 v4, s66
	v_mov_b32_e32 v5, s67
	ds_write_b64 v2, v[4:5]
	v_mov_b32_e32 v1, 0
	s_waitcnt vmcnt(0) lgkmcnt(0)
	v_readlane_b32 s56, v244, 40
	v_readlane_b32 s57, v244, 41
	v_readlane_b32 s58, v244, 42
	v_readlane_b32 s59, v244, 43
	v_readlane_b32 s60, v244, 44
	v_readlane_b32 s61, v244, 45
	v_readlane_b32 s62, v244, 46
	v_readlane_b32 s63, v244, 47
	v_readlane_b32 s64, v244, 48
	v_readlane_b32 s65, v244, 49
	v_readlane_b32 s66, v244, 50
	v_readlane_b32 s67, v244, 51
	v_readlane_b32 s68, v244, 52
	v_readlane_b32 s69, v244, 53
	v_readlane_b32 s70, v244, 54
	v_readlane_b32 s71, v244, 55
	v_readlane_b32 s44, v235, 8
	v_readlane_b32 s45, v235, 9
	s_branch .LBB0_720
